# P6 de-phasing of the 106 five-tile workgroups in four sub-groups: start delays 5 / 10 / 15 / 20 us (was one group at 15 us)
# speedup vs baseline: 1.0077x; 1.0001x over previous
.LBB0_2350:
	s_or_b64 exec, exec, s[0:1]
	s_add_u32 s4, s90, 0xa06ea00
	s_addc_u32 s5, s91, 0
	s_add_u32 s97, s90, 0x800000
	s_addc_u32 s2, s91, 0
	v_mov_b32_e32 v2, v0
	s_cmpk_gt_i32 s96, 0x595
	s_waitcnt lgkmcnt(0)
	s_barrier
	s_cbranch_scc1 .LBB0_2467
	s_cmpk_lt_u32 s96, 0x96
	s_cbranch_scc1 .Lstg6_done
	s_and_b32 s0, s96, 3
	s_add_i32 s0, s0, 1
.Lstg6_loop:
	s_sleep 127
	s_sleep 60
	s_sub_i32 s0, s0, 1
	s_cmp_lg_u32 s0, 0
	s_cbranch_scc1 .Lstg6_loop
